# ffn_dn -> rmsnorm phase overlap: finished row tiles are normalised by blocks that ran out of GEMM tiles (completion counters + unit queue), k=3 phase empty
# speedup vs baseline: 1.0006x; 1.0006x over previous
; __device__ __forceinline__ void phase_resid_gemm(const Params& p, const bf16_t* A, int lda, const bf16_t* Wt, int K, int l, int gate_k, float scale,
;                                  bool from_input, int mrows, char* smem, unsigned* tk) {
;     ...
;     const int bi = mod_idx(tm * 128);
;     const float* gate = mods_ptr(p, l, bi, gate_k);
;     const int row0 = tm * 128 + wr * 64 + fr, col0 = tn * 128 + wc * 64 + fq * 4;
;     const float* xi = xrow_ptr(p, from_input, row0) + col0;
;     float* xo = xrow_out(p, row0) + col0;
;     float4 gv[4];
; #pragma unroll
;     for (int n = 0; n < 4; ++n) {
;       gv[n] = *(const float4*)(gate + col0 + n * 16);
;       gv[n].x *= scale; gv[n].y *= scale; gv[n].z *= scale; gv[n].w *= scale;
;     }
; #pragma unroll
;     for (int m = 0; m < 4; ++m) {
; #pragma unroll
;       for (int n = 0; n < 4; ++n) {
;         const float4 xv = *(const float4*)(xi + (m * 16) * DM + n * 16);
;         float4 ov;
;         ov.x = xv.x + gv[n].x * acc[m][n][0];
;         ov.y = xv.y + gv[n].y * acc[m][n][1];
;         ov.z = xv.z + gv[n].z * acc[m][n][2];
;         ov.w = xv.w + gv[n].w * acc[m][n][3];
;         *(float4*)(xo + (m * 16) * DM + n * 16) = ov;
;       }
.Lrs_tk1:
	s_or_b64 exec, exec, s[48:49]
	s_waitcnt lgkmcnt(0)
	s_barrier
	ds_read_b32 v0, v1
	s_waitcnt lgkmcnt(0)
	v_readfirstlane_b32 s44, v0
	s_barrier
	s_lshr_b32 s68, s47, 3
	s_sub_i32 s45, s47, 128
	s_add_u32 s66, s100, 0x3380000
	s_addc_u32 s67, s101, 0
	s_cmp_lt_u32 s47, 128
	s_cselect_b32 s45, s47, s45
	s_cselect_b32 s34, s96, s66
	s_cselect_b32 s35, s97, s67
	s_cselect_b32 s66, s60, s64
	s_cselect_b32 s67, s61, s65
	s_cselect_b32 s68, s68, 16
	s_lshl_b32 s45, s45, 20
	s_lshl_b32 s49, s98, 9
	s_add_u32 s45, s45, s49
	s_add_u32 s34, s34, s45
	s_addc_u32 s35, s35, 0
	s_add_u32 s66, s66, s45
	s_addc_u32 s67, s67, 0
	s_cmp_eq_u32 s57, 1
	s_cselect_b32 s66, s66, s34
	s_cselect_b32 s67, s67, s35
	s_add_i32 s68, s68, s56
	s_mul_i32 s68, s68, 9
	s_add_i32 s68, s68, s55
	s_lshl_b32 s68, s68, 12
	s_add_u32 s68, s68, s49
	s_add_u32 s48, s100, 0x1e2a0000
	s_addc_u32 s49, s101, 0
	s_add_u32 s48, s48, s68
	s_addc_u32 s49, s49, 0
	global_load_dwordx4 v[136:139], v237, s[48:49]
	global_load_dwordx4 v[140:143], v237, s[48:49] offset:64
	global_load_dwordx4 v[144:147], v237, s[48:49] offset:128
	global_load_dwordx4 v[148:151], v237, s[48:49] offset:192
	global_load_dwordx4 v[196:199], v234, s[66:67]
	global_load_dwordx4 v[200:203], v234, s[66:67] offset:64
	global_load_dwordx4 v[204:207], v234, s[66:67] offset:128
	global_load_dwordx4 v[208:211], v234, s[66:67] offset:192
	s_add_u32 s66, s66, 0x10000
	s_addc_u32 s67, s67, 0
	global_load_dwordx4 v[212:215], v234, s[66:67]
	global_load_dwordx4 v[216:219], v234, s[66:67] offset:64
	global_load_dwordx4 v[220:223], v234, s[66:67] offset:128
	global_load_dwordx4 v[224:227], v234, s[66:67] offset:192
	s_add_u32 s66, s66, 0x10000
	s_addc_u32 s67, s67, 0
	s_waitcnt vmcnt(4)
	v_mul_f32_e32 v136, v246, v136
	v_mul_f32_e32 v137, v246, v137
	v_mul_f32_e32 v138, v246, v138
	v_mul_f32_e32 v139, v246, v139
	v_mul_f32_e32 v140, v246, v140
	v_mul_f32_e32 v141, v246, v141
	v_mul_f32_e32 v142, v246, v142
	v_mul_f32_e32 v143, v246, v143
	v_mul_f32_e32 v144, v246, v144
	v_mul_f32_e32 v145, v246, v145
	v_mul_f32_e32 v146, v246, v146
	v_mul_f32_e32 v147, v246, v147
	v_mul_f32_e32 v148, v246, v148
	v_mul_f32_e32 v149, v246, v149
	v_mul_f32_e32 v150, v246, v150
	v_mul_f32_e32 v151, v246, v151
	v_fma_f32 v2, v2, v136, v196
	v_fma_f32 v3, v3, v137, v197
	v_fma_f32 v4, v4, v138, v198
	v_fma_f32 v5, v5, v139, v199
	v_fma_f32 v6, v6, v140, v200
	v_fma_f32 v7, v7, v141, v201
	v_fma_f32 v8, v8, v142, v202
	v_fma_f32 v9, v9, v143, v203
	v_fma_f32 v10, v10, v144, v204
	v_fma_f32 v11, v11, v145, v205
	v_fma_f32 v12, v12, v146, v206
	v_fma_f32 v13, v13, v147, v207
	v_fma_f32 v14, v14, v148, v208
	v_fma_f32 v15, v15, v149, v209
	v_fma_f32 v16, v16, v150, v210
	v_fma_f32 v17, v17, v151, v211
	global_store_dwordx4 v234, v[2:5], s[34:35] sc1
	global_store_dwordx4 v234, v[6:9], s[34:35] offset:64 sc1
	global_store_dwordx4 v234, v[10:13], s[34:35] offset:128 sc1
	global_store_dwordx4 v234, v[14:17], s[34:35] offset:192 sc1
	s_add_u32 s34, s34, 0x10000
	s_addc_u32 s35, s35, 0
	global_load_dwordx4 v[196:199], v234, s[66:67]
	global_load_dwordx4 v[200:203], v234, s[66:67] offset:64
	global_load_dwordx4 v[204:207], v234, s[66:67] offset:128
	global_load_dwordx4 v[208:211], v234, s[66:67] offset:192
	s_add_u32 s66, s66, 0x10000
	s_addc_u32 s67, s67, 0
	s_waitcnt vmcnt(8)
	v_fma_f32 v18, v18, v136, v212
	v_fma_f32 v19, v19, v137, v213
	v_fma_f32 v20, v20, v138, v214
	v_fma_f32 v21, v21, v139, v215
	v_fma_f32 v22, v22, v140, v216
	v_fma_f32 v23, v23, v141, v217
	v_fma_f32 v24, v24, v142, v218
	v_fma_f32 v25, v25, v143, v219
	v_fma_f32 v26, v26, v144, v220
	v_fma_f32 v27, v27, v145, v221
	v_fma_f32 v28, v28, v146, v222
	v_fma_f32 v29, v29, v147, v223
	v_fma_f32 v30, v30, v148, v224
	v_fma_f32 v31, v31, v149, v225
	v_fma_f32 v32, v32, v150, v226
	v_fma_f32 v33, v33, v151, v227
	global_store_dwordx4 v234, v[18:21], s[34:35] sc1
	global_store_dwordx4 v234, v[22:25], s[34:35] offset:64 sc1
	global_store_dwordx4 v234, v[26:29], s[34:35] offset:128 sc1
	global_store_dwordx4 v234, v[30:33], s[34:35] offset:192 sc1
	s_add_u32 s34, s34, 0x10000
	s_addc_u32 s35, s35, 0
	global_load_dwordx4 v[212:215], v234, s[66:67]
	global_load_dwordx4 v[216:219], v234, s[66:67] offset:64
	global_load_dwordx4 v[220:223], v234, s[66:67] offset:128
	global_load_dwordx4 v[224:227], v234, s[66:67] offset:192
	s_add_u32 s66, s66, 0x10000
	s_addc_u32 s67, s67, 0
	s_waitcnt vmcnt(8)
	v_fma_f32 v34, v34, v136, v196
	v_fma_f32 v35, v35, v137, v197
	v_fma_f32 v36, v36, v138, v198
	v_fma_f32 v37, v37, v139, v199
	v_fma_f32 v38, v38, v140, v200
	v_fma_f32 v39, v39, v141, v201
	v_fma_f32 v40, v40, v142, v202
	v_fma_f32 v41, v41, v143, v203
	v_fma_f32 v42, v42, v144, v204
	v_fma_f32 v43, v43, v145, v205
	v_fma_f32 v44, v44, v146, v206
	v_fma_f32 v45, v45, v147, v207
	v_fma_f32 v46, v46, v148, v208
	v_fma_f32 v47, v47, v149, v209
	v_fma_f32 v48, v48, v150, v210
	v_fma_f32 v49, v49, v151, v211
	global_store_dwordx4 v234, v[34:37], s[34:35] sc1
	global_store_dwordx4 v234, v[38:41], s[34:35] offset:64 sc1
	global_store_dwordx4 v234, v[42:45], s[34:35] offset:128 sc1
	global_store_dwordx4 v234, v[46:49], s[34:35] offset:192 sc1
	s_add_u32 s34, s34, 0x10000
	s_addc_u32 s35, s35, 0
	global_load_dwordx4 v[196:199], v234, s[66:67]
	global_load_dwordx4 v[200:203], v234, s[66:67] offset:64
	global_load_dwordx4 v[204:207], v234, s[66:67] offset:128
	global_load_dwordx4 v[208:211], v234, s[66:67] offset:192
	s_add_u32 s66, s66, 0x10000
	s_addc_u32 s67, s67, 0
	s_waitcnt vmcnt(8)
; __device__ __forceinline__ void phase_resid_gemm(const Params& p, const bf16_t* A, int lda, const bf16_t* Wt, int K, int l, int gate_k, float scale,
;                                  bool from_input, int mrows, char* smem, unsigned* tk) {
;     ...
; #pragma unroll
;     for (int m = 0; m < 4; ++m) {
; #pragma unroll
;       for (int n = 0; n < 4; ++n) {
;         const float4 xv = *(const float4*)(xi + (m * 16) * DM + n * 16);
;         float4 ov;
;         ov.x = xv.x + gv[n].x * acc[m][n][0];
;         ov.y = xv.y + gv[n].y * acc[m][n][1];
;         ov.z = xv.z + gv[n].z * acc[m][n][2];
;         ov.w = xv.w + gv[n].w * acc[m][n][3];
;         *(float4*)(xo + (m * 16) * DM + n * 16) = ov;
;       }
;       __builtin_amdgcn_sched_barrier(0);
;     }
	v_fma_f32 v50, v50, v136, v212
	v_fma_f32 v51, v51, v137, v213
	v_fma_f32 v52, v52, v138, v214
	v_fma_f32 v53, v53, v139, v215
	v_fma_f32 v54, v54, v140, v216
	v_fma_f32 v55, v55, v141, v217
	v_fma_f32 v56, v56, v142, v218
	v_fma_f32 v57, v57, v143, v219
	v_fma_f32 v58, v58, v144, v220
	v_fma_f32 v59, v59, v145, v221
	v_fma_f32 v60, v60, v146, v222
	v_fma_f32 v61, v61, v147, v223
	v_fma_f32 v62, v62, v148, v224
	v_fma_f32 v63, v63, v149, v225
	v_fma_f32 v64, v64, v150, v226
	v_fma_f32 v65, v65, v151, v227
	global_store_dwordx4 v234, v[50:53], s[34:35] sc1
	global_store_dwordx4 v234, v[54:57], s[34:35] offset:64 sc1
	global_store_dwordx4 v234, v[58:61], s[34:35] offset:128 sc1
	global_store_dwordx4 v234, v[62:65], s[34:35] offset:192 sc1
	s_add_u32 s34, s34, 0x10000
	s_addc_u32 s35, s35, 0
	global_load_dwordx4 v[212:215], v234, s[66:67]
	global_load_dwordx4 v[216:219], v234, s[66:67] offset:64
	global_load_dwordx4 v[220:223], v234, s[66:67] offset:128
	global_load_dwordx4 v[224:227], v234, s[66:67] offset:192
	s_add_u32 s66, s66, 0x10000
	s_addc_u32 s67, s67, 0
	s_waitcnt vmcnt(8)
	v_fma_f32 v66, v66, v136, v196
	v_fma_f32 v67, v67, v137, v197
	v_fma_f32 v68, v68, v138, v198
	v_fma_f32 v69, v69, v139, v199
	v_fma_f32 v70, v70, v140, v200
	v_fma_f32 v71, v71, v141, v201
	v_fma_f32 v72, v72, v142, v202
	v_fma_f32 v73, v73, v143, v203
	v_fma_f32 v74, v74, v144, v204
	v_fma_f32 v75, v75, v145, v205
	v_fma_f32 v76, v76, v146, v206
	v_fma_f32 v77, v77, v147, v207
	v_fma_f32 v78, v78, v148, v208
	v_fma_f32 v79, v79, v149, v209
	v_fma_f32 v80, v80, v150, v210
	v_fma_f32 v81, v81, v151, v211
	global_store_dwordx4 v234, v[66:69], s[34:35] sc1
	global_store_dwordx4 v234, v[70:73], s[34:35] offset:64 sc1
	global_store_dwordx4 v234, v[74:77], s[34:35] offset:128 sc1
	global_store_dwordx4 v234, v[78:81], s[34:35] offset:192 sc1
	s_add_u32 s34, s34, 0x10000
	s_addc_u32 s35, s35, 0
	global_load_dwordx4 v[196:199], v234, s[66:67]
	global_load_dwordx4 v[200:203], v234, s[66:67] offset:64
	global_load_dwordx4 v[204:207], v234, s[66:67] offset:128
	global_load_dwordx4 v[208:211], v234, s[66:67] offset:192
	s_add_u32 s66, s66, 0x10000
	s_addc_u32 s67, s67, 0
	s_waitcnt vmcnt(8)
	v_fma_f32 v82, v82, v136, v212
	v_fma_f32 v83, v83, v137, v213
	v_fma_f32 v84, v84, v138, v214
	v_fma_f32 v85, v85, v139, v215
	v_fma_f32 v86, v86, v140, v216
	v_fma_f32 v87, v87, v141, v217
	v_fma_f32 v88, v88, v142, v218
	v_fma_f32 v89, v89, v143, v219
	v_fma_f32 v92, v92, v144, v220
	v_fma_f32 v93, v93, v145, v221
	v_fma_f32 v94, v94, v146, v222
	v_fma_f32 v95, v95, v147, v223
	v_fma_f32 v96, v96, v148, v224
	v_fma_f32 v97, v97, v149, v225
	v_fma_f32 v98, v98, v150, v226
	v_fma_f32 v99, v99, v151, v227
	global_store_dwordx4 v234, v[82:85], s[34:35] sc1
	global_store_dwordx4 v234, v[86:89], s[34:35] offset:64 sc1
	global_store_dwordx4 v234, v[92:95], s[34:35] offset:128 sc1
	global_store_dwordx4 v234, v[96:99], s[34:35] offset:192 sc1
	s_add_u32 s34, s34, 0x10000
	s_addc_u32 s35, s35, 0
	global_load_dwordx4 v[212:215], v234, s[66:67]
	global_load_dwordx4 v[216:219], v234, s[66:67] offset:64
	global_load_dwordx4 v[220:223], v234, s[66:67] offset:128
	global_load_dwordx4 v[224:227], v234, s[66:67] offset:192
	s_add_u32 s66, s66, 0x10000
	s_addc_u32 s67, s67, 0
	s_waitcnt vmcnt(8)
	v_fma_f32 v100, v100, v136, v196
	v_fma_f32 v101, v101, v137, v197
	v_fma_f32 v102, v102, v138, v198
	v_fma_f32 v103, v103, v139, v199
	v_fma_f32 v104, v104, v140, v200
	v_fma_f32 v105, v105, v141, v201
	v_fma_f32 v106, v106, v142, v202
	v_fma_f32 v107, v107, v143, v203
	v_fma_f32 v108, v108, v144, v204
	v_fma_f32 v109, v109, v145, v205
	v_fma_f32 v110, v110, v146, v206
	v_fma_f32 v111, v111, v147, v207
	v_fma_f32 v112, v112, v148, v208
	v_fma_f32 v113, v113, v149, v209
	v_fma_f32 v114, v114, v150, v210
	v_fma_f32 v115, v115, v151, v211
	global_store_dwordx4 v234, v[100:103], s[34:35] sc1
	global_store_dwordx4 v234, v[104:107], s[34:35] offset:64 sc1
	global_store_dwordx4 v234, v[108:111], s[34:35] offset:128 sc1
	global_store_dwordx4 v234, v[112:115], s[34:35] offset:192 sc1
	s_add_u32 s34, s34, 0x10000
	s_addc_u32 s35, s35, 0
	s_waitcnt vmcnt(4)
	v_fma_f32 v116, v116, v136, v212
	v_fma_f32 v117, v117, v137, v213
	v_fma_f32 v118, v118, v138, v214
	v_fma_f32 v119, v119, v139, v215
	v_fma_f32 v120, v120, v140, v216
	v_fma_f32 v121, v121, v141, v217
	v_fma_f32 v122, v122, v142, v218
	v_fma_f32 v123, v123, v143, v219
	v_fma_f32 v124, v124, v144, v220
	v_fma_f32 v125, v125, v145, v221
	v_fma_f32 v126, v126, v146, v222
	v_fma_f32 v127, v127, v147, v223
	v_fma_f32 v128, v128, v148, v224
	v_fma_f32 v129, v129, v149, v225
	v_fma_f32 v130, v130, v150, v226
	v_fma_f32 v131, v131, v151, v227
	global_store_dwordx4 v234, v[116:119], s[34:35] sc1
	global_store_dwordx4 v234, v[120:123], s[34:35] offset:64 sc1
	global_store_dwordx4 v234, v[124:127], s[34:35] offset:128 sc1
	global_store_dwordx4 v234, v[128:131], s[34:35] offset:192 sc1
	s_add_u32 s34, s34, 0x10000
	s_addc_u32 s35, s35, 0
	s_cmp_lg_u32 s77, 2
	s_cbranch_scc1 .Lrs_nosig
	s_waitcnt vmcnt(0)
	s_barrier
	s_and_saveexec_b64 s[48:49], s[62:63]
	s_cbranch_execz .Lrs_sig1
	s_cmp_gt_u32 s91, 13
	s_cselect_b32 s45, 3824, 16
	s_add_i32 s45, s45, s47
	s_lshl_b32 s45, s45, 2
	s_add_i32 s45, s45, 0x1e3d2000
	v_mov_b32_e32 v0, 1
	v_mov_b32_e32 v238, s45
	global_atomic_add v238, v0, s[100:101]
.Lrs_sig1:
	s_or_b64 exec, exec, s[48:49]
.Lrs_nosig:
	s_branch .Lrs_tile
; __device__ __forceinline__ void phase_norm(const Params& p, int l, int which, int nrows) {
;     ...
;   for (int r = r0; r < r1; ++r) {
;     const float* xr = xrow_ptr(p, from_input, r);
;     const int bi = mod_idx(r);
;     if (bi != cur_bi) {
;       const float* sh = mods_ptr(p, l, bi, which * 3);
; #pragma unroll
;       for (int i = 0; i < 4; ++i) { s4[i] = *(const float4*)(sh + i * 256 + lane * 4); c4[i] = *(const float4*)(sh + 1024 + i * 256 + lane * 4); }
;       cur_bi = bi;
;     }
;     float4 v[4];
;     float ss = 0.f;
; #pragma unroll
;     for (int i = 0; i < 4; ++i) {
;       v[i] = *(const float4*)(xr + i * 256 + lane * 4);
;       ss += v[i].x * v[i].x + v[i].y * v[i].y + v[i].z * v[i].z + v[i].w * v[i].w;
;     }
.Lrs_exit:
	s_cmp_lg_u32 s77, 2
	s_cbranch_scc1 .Lnu_done
	s_waitcnt vmcnt(0) lgkmcnt(0)
	s_load_dwordx2 s[44:45], s[0:1], 0x30
	s_cmp_gt_u32 s91, 13
	s_cselect_b32 s40, 3824, 16
	s_cselect_b32 s42, 17, 0
	s_cselect_b32 s43, 4, 1
	s_lshl_b32 s43, s43, 12
	s_lshl_b32 s40, s40, 2
	s_add_i32 s40, s40, 0x1e3d2000
	s_add_i32 s41, s40, 0x240
	s_waitcnt lgkmcnt(0)
	s_add_u32 s44, s44, s43
	s_addc_u32 s45, s45, 0
	v_and_b32_e32 v241, 63, v172
	v_lshlrev_b32_e32 v240, 4, v241
	v_lshlrev_b32_e32 v241, 3, v241
.Lnu_next:
	s_and_saveexec_b64 s[48:49], s[62:63]
	s_cbranch_execz .Lnu_t0
	v_mov_b32_e32 v0, 1
	v_mov_b32_e32 v238, s41
	global_atomic_add v239, v238, v0, s[100:101] sc0
	s_waitcnt vmcnt(0)
	ds_write_b32 v1, v239
.Lnu_t0:
	s_or_b64 exec, exec, s[48:49]
	s_waitcnt lgkmcnt(0)
	s_barrier
	ds_read_b32 v0, v1
	s_waitcnt lgkmcnt(0)
	v_readfirstlane_b32 s50, v0
	s_barrier
	s_cmpk_ge_u32 s50, 0x480
	s_cbranch_scc1 .Lnu_done
	s_lshr_b32 s51, s50, 7
	s_and_b32 s52, s50, 127
	s_lshr_b32 s53, s52, 4
	s_bfe_u32 s54, s52, 0x10003
	s_and_b32 s55, s52, 7
	s_lshl_b32 s51, s51, 3
	s_add_i32 s51, s51, s53
	s_lshl_b32 s51, s51, 1
	s_add_i32 s47, s51, s54
	s_lshl_b32 s51, s47, 2
	s_add_i32 s51, s51, s40
	v_mov_b32_e32 v238, s51
.Lnu_poll:
	global_load_dword v239, v238, s[100:101] sc1
	s_waitcnt vmcnt(0)
	v_readfirstlane_b32 s52, v239
	s_cmp_ge_u32 s52, 8
	s_cbranch_scc1 .Lnu_go
	s_sleep 8
	s_branch .Lnu_poll
.Lnu_go:
	buffer_inv sc1
	s_lshl_b32 s51, s47, 8
	s_lshl_b32 s52, s55, 5
	s_add_i32 s51, s51, s52
	s_lshr_b32 s52, s46, 7
	s_add_i32 s51, s51, s52
	s_sub_i32 s52, s51, 0x8000
	s_add_u32 s56, s100, 0x3380000
	s_addc_u32 s57, s101, 0
	s_lshr_b32 s58, s47, 3
	s_cmp_lt_u32 s47, 128
	s_cselect_b32 s52, s51, s52
	s_cselect_b32 s56, s96, s56
	s_cselect_b32 s57, s97, s57
	s_cselect_b32 s58, s58, 16
	s_lshl_b32 s52, s52, 12
	s_add_u32 s56, s56, s52
	s_addc_u32 s57, s57, 0
	s_lshl_b32 s52, s51, 11
	s_add_u32 s64, s100, 0x4380000
	s_addc_u32 s65, s101, 0
	s_add_u32 s64, s64, s52
	s_addc_u32 s65, s65, 0
	s_add_i32 s58, s58, s42
	s_mul_i32 s58, s58, 9
	s_add_i32 s58, s58, 3
	s_lshl_b32 s58, s58, 12
	s_add_u32 s60, s100, 0x1e2a0000
	s_addc_u32 s61, s101, 0
	s_add_u32 s60, s60, s58
	s_addc_u32 s61, s61, 0
	s_add_u32 s66, s60, 0x1000
	s_addc_u32 s67, s61, 0
	global_load_dwordx4 v[136:139], v240, s[44:45]
	global_load_dwordx4 v[140:143], v240, s[44:45] offset:1024
	global_load_dwordx4 v[144:147], v240, s[44:45] offset:2048
	global_load_dwordx4 v[148:151], v240, s[44:45] offset:3072
	global_load_dwordx4 v[152:155], v240, s[60:61]
	global_load_dwordx4 v[156:159], v240, s[60:61] offset:1024
	global_load_dwordx4 v[160:163], v240, s[60:61] offset:2048
	global_load_dwordx4 v[164:167], v240, s[60:61] offset:3072
	global_load_dwordx4 v[196:199], v240, s[66:67]
	global_load_dwordx4 v[200:203], v240, s[66:67] offset:1024
	global_load_dwordx4 v[204:207], v240, s[66:67] offset:2048
	global_load_dwordx4 v[208:211], v240, s[66:67] offset:3072
	global_load_dwordx4 v[2:5], v240, s[56:57] sc1
	global_load_dwordx4 v[6:9], v240, s[56:57] offset:1024 sc1
	global_load_dwordx4 v[10:13], v240, s[56:57] offset:2048 sc1
	global_load_dwordx4 v[14:17], v240, s[56:57] offset:3072 sc1
	s_add_u32 s56, s56, 0x1000
	s_addc_u32 s57, s57, 0
	global_load_dwordx4 v[18:21], v240, s[56:57] sc1
	global_load_dwordx4 v[22:25], v240, s[56:57] offset:1024 sc1
	global_load_dwordx4 v[26:29], v240, s[56:57] offset:2048 sc1
	global_load_dwordx4 v[30:33], v240, s[56:57] offset:3072 sc1
	s_add_u32 s56, s56, 0x1000
	s_addc_u32 s57, s57, 0
	global_load_dwordx4 v[34:37], v240, s[56:57] sc1
	global_load_dwordx4 v[38:41], v240, s[56:57] offset:1024 sc1
	global_load_dwordx4 v[42:45], v240, s[56:57] offset:2048 sc1
	global_load_dwordx4 v[46:49], v240, s[56:57] offset:3072 sc1
	s_add_u32 s56, s56, 0x1000
	s_addc_u32 s57, s57, 0
	global_load_dwordx4 v[50:53], v240, s[56:57] sc1
	global_load_dwordx4 v[54:57], v240, s[56:57] offset:1024 sc1
	global_load_dwordx4 v[58:61], v240, s[56:57] offset:2048 sc1
	global_load_dwordx4 v[62:65], v240, s[56:57] offset:3072 sc1
	s_add_u32 s56, s56, 0x1000
	s_addc_u32 s57, s57, 0
	global_load_dwordx4 v[66:69], v240, s[56:57] sc1
	global_load_dwordx4 v[70:73], v240, s[56:57] offset:1024 sc1
	global_load_dwordx4 v[74:77], v240, s[56:57] offset:2048 sc1
	global_load_dwordx4 v[78:81], v240, s[56:57] offset:3072 sc1
	s_add_u32 s56, s56, 0x1000
	s_addc_u32 s57, s57, 0
	global_load_dwordx4 v[82:85], v240, s[56:57] sc1
	global_load_dwordx4 v[86:89], v240, s[56:57] offset:1024 sc1
	global_load_dwordx4 v[92:95], v240, s[56:57] offset:2048 sc1
	global_load_dwordx4 v[96:99], v240, s[56:57] offset:3072 sc1
	s_add_u32 s56, s56, 0x1000
	s_addc_u32 s57, s57, 0
	global_load_dwordx4 v[100:103], v240, s[56:57] sc1
	global_load_dwordx4 v[104:107], v240, s[56:57] offset:1024 sc1
	global_load_dwordx4 v[108:111], v240, s[56:57] offset:2048 sc1
	global_load_dwordx4 v[112:115], v240, s[56:57] offset:3072 sc1
	s_add_u32 s56, s56, 0x1000
	s_addc_u32 s57, s57, 0
	global_load_dwordx4 v[116:119], v240, s[56:57] sc1
	global_load_dwordx4 v[120:123], v240, s[56:57] offset:1024 sc1
	global_load_dwordx4 v[124:127], v240, s[56:57] offset:2048 sc1
	global_load_dwordx4 v[128:131], v240, s[56:57] offset:3072 sc1
	s_waitcnt vmcnt(32)
	v_pk_add_f32 v[196:197], v[196:197], 1.0 op_sel_hi:[1,0]
	v_pk_add_f32 v[198:199], v[198:199], 1.0 op_sel_hi:[1,0]
	v_pk_add_f32 v[200:201], v[200:201], 1.0 op_sel_hi:[1,0]
	v_pk_add_f32 v[202:203], v[202:203], 1.0 op_sel_hi:[1,0]
	v_pk_add_f32 v[204:205], v[204:205], 1.0 op_sel_hi:[1,0]
	v_pk_add_f32 v[206:207], v[206:207], 1.0 op_sel_hi:[1,0]
	v_pk_add_f32 v[208:209], v[208:209], 1.0 op_sel_hi:[1,0]
	v_pk_add_f32 v[210:211], v[210:211], 1.0 op_sel_hi:[1,0]
	s_waitcnt vmcnt(28)
; __device__ __forceinline__ void phase_norm(const Params& p, int l, int which, int nrows) {
;     ...
; #pragma unroll
;     for (int i = 0; i < 4; ++i) {
;       v[i] = *(const float4*)(xr + i * 256 + lane * 4);
;       ss += v[i].x * v[i].x + v[i].y * v[i].y + v[i].z * v[i].z + v[i].w * v[i].w;
;     }
;     ss = wave_sum(ss);
;     const float rstd = rsqrtf(ss * (1.f / 1024.f) + 1e-6f);
; #pragma unroll
;     for (int i = 0; i < 4; ++i) {
;       const int c = i * 256 + lane * 4;
;       const float y0 = (v[i].x * rstd * g4[i].x) * (1.f + c4[i].x) + s4[i].x;
;       const float y1 = (v[i].y * rstd * g4[i].y) * (1.f + c4[i].y) + s4[i].y;
;       const float y2 = (v[i].z * rstd * g4[i].z) * (1.f + c4[i].z) + s4[i].z;
;       const float y3 = (v[i].w * rstd * g4[i].w) * (1.f + c4[i].w) + s4[i].w;
;       u32x2 o; o.x = pack2(y0, y1); o.y = pack2(y2, y3);
;       *(u32x2*)(H + (size_t)r * DM + c) = o;
;     }
	v_pk_mul_f32 v[212:213], v[2:3], v[2:3]
	v_pk_fma_f32 v[212:213], v[4:5], v[4:5], v[212:213]
	v_pk_fma_f32 v[212:213], v[6:7], v[6:7], v[212:213]
	v_pk_fma_f32 v[212:213], v[8:9], v[8:9], v[212:213]
	v_pk_fma_f32 v[212:213], v[10:11], v[10:11], v[212:213]
	v_pk_fma_f32 v[212:213], v[12:13], v[12:13], v[212:213]
	v_pk_fma_f32 v[212:213], v[14:15], v[14:15], v[212:213]
	v_pk_fma_f32 v[212:213], v[16:17], v[16:17], v[212:213]
	v_add_f32_e32 v214, v212, v213
	s_nop 1
	v_add_f32_dpp v214, v214, v214 quad_perm:[1,0,3,2] row_mask:0xf bank_mask:0xf
	s_nop 1
	v_add_f32_dpp v214, v214, v214 quad_perm:[2,3,0,1] row_mask:0xf bank_mask:0xf
	s_nop 1
	v_add_f32_dpp v214, v214, v214 row_half_mirror row_mask:0xf bank_mask:0xf
	s_nop 1
	v_add_f32_dpp v214, v214, v214 row_mirror row_mask:0xf bank_mask:0xf
	s_nop 1
	v_readlane_b32 vcc_lo, v214, 0
	v_readlane_b32 vcc_hi, v214, 16
	s_nop 1
	v_mov_b32_e32 v216, vcc_lo
	v_add_f32_e32 v216, vcc_hi, v216
	v_readlane_b32 vcc_lo, v214, 32
	v_readlane_b32 vcc_hi, v214, 48
	s_nop 1
	v_add_f32_e32 v216, vcc_lo, v216
	v_add_f32_e32 v216, vcc_hi, v216
	v_fmamk_f32 v216, v216, 0x3a800000, v174
	v_rsq_f32_e32 v216, v216
	s_nop 0
	v_pk_mul_f32 v[2:3], v[2:3], v[216:217] op_sel_hi:[1,0]
	v_pk_mul_f32 v[4:5], v[4:5], v[216:217] op_sel_hi:[1,0]
	v_pk_mul_f32 v[6:7], v[6:7], v[216:217] op_sel_hi:[1,0]
	v_pk_mul_f32 v[8:9], v[8:9], v[216:217] op_sel_hi:[1,0]
	v_pk_mul_f32 v[10:11], v[10:11], v[216:217] op_sel_hi:[1,0]
	v_pk_mul_f32 v[12:13], v[12:13], v[216:217] op_sel_hi:[1,0]
	v_pk_mul_f32 v[14:15], v[14:15], v[216:217] op_sel_hi:[1,0]
	v_pk_mul_f32 v[16:17], v[16:17], v[216:217] op_sel_hi:[1,0]
	v_pk_mul_f32 v[2:3], v[136:137], v[2:3]
	v_pk_mul_f32 v[4:5], v[138:139], v[4:5]
	v_pk_mul_f32 v[6:7], v[140:141], v[6:7]
	v_pk_mul_f32 v[8:9], v[142:143], v[8:9]
	v_pk_mul_f32 v[10:11], v[144:145], v[10:11]
	v_pk_mul_f32 v[12:13], v[146:147], v[12:13]
	v_pk_mul_f32 v[14:15], v[148:149], v[14:15]
	v_pk_mul_f32 v[16:17], v[150:151], v[16:17]
	v_pk_fma_f32 v[2:3], v[196:197], v[2:3], v[152:153]
	v_pk_fma_f32 v[4:5], v[198:199], v[4:5], v[154:155]
	v_pk_fma_f32 v[6:7], v[200:201], v[6:7], v[156:157]
	v_pk_fma_f32 v[8:9], v[202:203], v[8:9], v[158:159]
	v_pk_fma_f32 v[10:11], v[204:205], v[10:11], v[160:161]
	v_pk_fma_f32 v[12:13], v[206:207], v[12:13], v[162:163]
	v_pk_fma_f32 v[14:15], v[208:209], v[14:15], v[164:165]
	v_pk_fma_f32 v[16:17], v[210:211], v[16:17], v[166:167]
	v_cvt_pk_bf16_f32 v2, v2, v3
	v_cvt_pk_bf16_f32 v3, v4, v5
	global_store_dwordx2 v241, v[2:3], s[64:65]
	v_cvt_pk_bf16_f32 v6, v6, v7
	v_cvt_pk_bf16_f32 v7, v8, v9
	global_store_dwordx2 v241, v[6:7], s[64:65] offset:512
	v_cvt_pk_bf16_f32 v10, v10, v11
	v_cvt_pk_bf16_f32 v11, v12, v13
	global_store_dwordx2 v241, v[10:11], s[64:65] offset:1024
	v_cvt_pk_bf16_f32 v14, v14, v15
	v_cvt_pk_bf16_f32 v15, v16, v17
	global_store_dwordx2 v241, v[14:15], s[64:65] offset:1536
	s_add_u32 s64, s64, 0x800
	s_addc_u32 s65, s65, 0
	s_waitcnt vmcnt(28)
	v_pk_mul_f32 v[212:213], v[18:19], v[18:19]
	v_pk_fma_f32 v[212:213], v[20:21], v[20:21], v[212:213]
	v_pk_fma_f32 v[212:213], v[22:23], v[22:23], v[212:213]
	v_pk_fma_f32 v[212:213], v[24:25], v[24:25], v[212:213]
	v_pk_fma_f32 v[212:213], v[26:27], v[26:27], v[212:213]
	v_pk_fma_f32 v[212:213], v[28:29], v[28:29], v[212:213]
	v_pk_fma_f32 v[212:213], v[30:31], v[30:31], v[212:213]
	v_pk_fma_f32 v[212:213], v[32:33], v[32:33], v[212:213]
	v_add_f32_e32 v214, v212, v213
	s_nop 1
	v_add_f32_dpp v214, v214, v214 quad_perm:[1,0,3,2] row_mask:0xf bank_mask:0xf
	s_nop 1
	v_add_f32_dpp v214, v214, v214 quad_perm:[2,3,0,1] row_mask:0xf bank_mask:0xf
	s_nop 1
	v_add_f32_dpp v214, v214, v214 row_half_mirror row_mask:0xf bank_mask:0xf
	s_nop 1
	v_add_f32_dpp v214, v214, v214 row_mirror row_mask:0xf bank_mask:0xf
	s_nop 1
	v_readlane_b32 vcc_lo, v214, 0
	v_readlane_b32 vcc_hi, v214, 16
	s_nop 1
	v_mov_b32_e32 v216, vcc_lo
	v_add_f32_e32 v216, vcc_hi, v216
	v_readlane_b32 vcc_lo, v214, 32
	v_readlane_b32 vcc_hi, v214, 48
	s_nop 1
	v_add_f32_e32 v216, vcc_lo, v216
	v_add_f32_e32 v216, vcc_hi, v216
	v_fmamk_f32 v216, v216, 0x3a800000, v174
	v_rsq_f32_e32 v216, v216
	s_nop 0
	v_pk_mul_f32 v[18:19], v[18:19], v[216:217] op_sel_hi:[1,0]
	v_pk_mul_f32 v[20:21], v[20:21], v[216:217] op_sel_hi:[1,0]
	v_pk_mul_f32 v[22:23], v[22:23], v[216:217] op_sel_hi:[1,0]
	v_pk_mul_f32 v[24:25], v[24:25], v[216:217] op_sel_hi:[1,0]
	v_pk_mul_f32 v[26:27], v[26:27], v[216:217] op_sel_hi:[1,0]
	v_pk_mul_f32 v[28:29], v[28:29], v[216:217] op_sel_hi:[1,0]
	v_pk_mul_f32 v[30:31], v[30:31], v[216:217] op_sel_hi:[1,0]
	v_pk_mul_f32 v[32:33], v[32:33], v[216:217] op_sel_hi:[1,0]
	v_pk_mul_f32 v[18:19], v[136:137], v[18:19]
	v_pk_mul_f32 v[20:21], v[138:139], v[20:21]
	v_pk_mul_f32 v[22:23], v[140:141], v[22:23]
	v_pk_mul_f32 v[24:25], v[142:143], v[24:25]
	v_pk_mul_f32 v[26:27], v[144:145], v[26:27]
	v_pk_mul_f32 v[28:29], v[146:147], v[28:29]
	v_pk_mul_f32 v[30:31], v[148:149], v[30:31]
	v_pk_mul_f32 v[32:33], v[150:151], v[32:33]
	v_pk_fma_f32 v[18:19], v[196:197], v[18:19], v[152:153]
	v_pk_fma_f32 v[20:21], v[198:199], v[20:21], v[154:155]
	v_pk_fma_f32 v[22:23], v[200:201], v[22:23], v[156:157]
	v_pk_fma_f32 v[24:25], v[202:203], v[24:25], v[158:159]
	v_pk_fma_f32 v[26:27], v[204:205], v[26:27], v[160:161]
	v_pk_fma_f32 v[28:29], v[206:207], v[28:29], v[162:163]
	v_pk_fma_f32 v[30:31], v[208:209], v[30:31], v[164:165]
	v_pk_fma_f32 v[32:33], v[210:211], v[32:33], v[166:167]
	v_cvt_pk_bf16_f32 v18, v18, v19
	v_cvt_pk_bf16_f32 v19, v20, v21
	global_store_dwordx2 v241, v[18:19], s[64:65]
	v_cvt_pk_bf16_f32 v22, v22, v23
	v_cvt_pk_bf16_f32 v23, v24, v25
	global_store_dwordx2 v241, v[22:23], s[64:65] offset:512
	v_cvt_pk_bf16_f32 v26, v26, v27
	v_cvt_pk_bf16_f32 v27, v28, v29
	global_store_dwordx2 v241, v[26:27], s[64:65] offset:1024
	v_cvt_pk_bf16_f32 v30, v30, v31
	v_cvt_pk_bf16_f32 v31, v32, v33
	global_store_dwordx2 v241, v[30:31], s[64:65] offset:1536
	s_add_u32 s64, s64, 0x800
	s_addc_u32 s65, s65, 0
	s_waitcnt vmcnt(28)
; __device__ __forceinline__ void phase_norm(const Params& p, int l, int which, int nrows) {
;     ...
; #pragma unroll
;     for (int i = 0; i < 4; ++i) {
;       v[i] = *(const float4*)(xr + i * 256 + lane * 4);
;       ss += v[i].x * v[i].x + v[i].y * v[i].y + v[i].z * v[i].z + v[i].w * v[i].w;
;     }
;     ss = wave_sum(ss);
;     const float rstd = rsqrtf(ss * (1.f / 1024.f) + 1e-6f);
; #pragma unroll
;     for (int i = 0; i < 4; ++i) {
;       const int c = i * 256 + lane * 4;
;       const float y0 = (v[i].x * rstd * g4[i].x) * (1.f + c4[i].x) + s4[i].x;
;       const float y1 = (v[i].y * rstd * g4[i].y) * (1.f + c4[i].y) + s4[i].y;
;       const float y2 = (v[i].z * rstd * g4[i].z) * (1.f + c4[i].z) + s4[i].z;
;       const float y3 = (v[i].w * rstd * g4[i].w) * (1.f + c4[i].w) + s4[i].w;
;       u32x2 o; o.x = pack2(y0, y1); o.y = pack2(y2, y3);
;       *(u32x2*)(H + (size_t)r * DM + c) = o;
;     }
	v_pk_mul_f32 v[212:213], v[34:35], v[34:35]
	v_pk_fma_f32 v[212:213], v[36:37], v[36:37], v[212:213]
	v_pk_fma_f32 v[212:213], v[38:39], v[38:39], v[212:213]
	v_pk_fma_f32 v[212:213], v[40:41], v[40:41], v[212:213]
	v_pk_fma_f32 v[212:213], v[42:43], v[42:43], v[212:213]
	v_pk_fma_f32 v[212:213], v[44:45], v[44:45], v[212:213]
	v_pk_fma_f32 v[212:213], v[46:47], v[46:47], v[212:213]
	v_pk_fma_f32 v[212:213], v[48:49], v[48:49], v[212:213]
	v_add_f32_e32 v214, v212, v213
	s_nop 1
	v_add_f32_dpp v214, v214, v214 quad_perm:[1,0,3,2] row_mask:0xf bank_mask:0xf
	s_nop 1
	v_add_f32_dpp v214, v214, v214 quad_perm:[2,3,0,1] row_mask:0xf bank_mask:0xf
	s_nop 1
	v_add_f32_dpp v214, v214, v214 row_half_mirror row_mask:0xf bank_mask:0xf
	s_nop 1
	v_add_f32_dpp v214, v214, v214 row_mirror row_mask:0xf bank_mask:0xf
	s_nop 1
	v_readlane_b32 vcc_lo, v214, 0
	v_readlane_b32 vcc_hi, v214, 16
	s_nop 1
	v_mov_b32_e32 v216, vcc_lo
	v_add_f32_e32 v216, vcc_hi, v216
	v_readlane_b32 vcc_lo, v214, 32
	v_readlane_b32 vcc_hi, v214, 48
	s_nop 1
	v_add_f32_e32 v216, vcc_lo, v216
	v_add_f32_e32 v216, vcc_hi, v216
	v_fmamk_f32 v216, v216, 0x3a800000, v174
	v_rsq_f32_e32 v216, v216
	s_nop 0
	v_pk_mul_f32 v[34:35], v[34:35], v[216:217] op_sel_hi:[1,0]
	v_pk_mul_f32 v[36:37], v[36:37], v[216:217] op_sel_hi:[1,0]
	v_pk_mul_f32 v[38:39], v[38:39], v[216:217] op_sel_hi:[1,0]
	v_pk_mul_f32 v[40:41], v[40:41], v[216:217] op_sel_hi:[1,0]
	v_pk_mul_f32 v[42:43], v[42:43], v[216:217] op_sel_hi:[1,0]
	v_pk_mul_f32 v[44:45], v[44:45], v[216:217] op_sel_hi:[1,0]
	v_pk_mul_f32 v[46:47], v[46:47], v[216:217] op_sel_hi:[1,0]
	v_pk_mul_f32 v[48:49], v[48:49], v[216:217] op_sel_hi:[1,0]
	v_pk_mul_f32 v[34:35], v[136:137], v[34:35]
	v_pk_mul_f32 v[36:37], v[138:139], v[36:37]
	v_pk_mul_f32 v[38:39], v[140:141], v[38:39]
	v_pk_mul_f32 v[40:41], v[142:143], v[40:41]
	v_pk_mul_f32 v[42:43], v[144:145], v[42:43]
	v_pk_mul_f32 v[44:45], v[146:147], v[44:45]
	v_pk_mul_f32 v[46:47], v[148:149], v[46:47]
	v_pk_mul_f32 v[48:49], v[150:151], v[48:49]
	v_pk_fma_f32 v[34:35], v[196:197], v[34:35], v[152:153]
	v_pk_fma_f32 v[36:37], v[198:199], v[36:37], v[154:155]
	v_pk_fma_f32 v[38:39], v[200:201], v[38:39], v[156:157]
	v_pk_fma_f32 v[40:41], v[202:203], v[40:41], v[158:159]
	v_pk_fma_f32 v[42:43], v[204:205], v[42:43], v[160:161]
	v_pk_fma_f32 v[44:45], v[206:207], v[44:45], v[162:163]
	v_pk_fma_f32 v[46:47], v[208:209], v[46:47], v[164:165]
	v_pk_fma_f32 v[48:49], v[210:211], v[48:49], v[166:167]
	v_cvt_pk_bf16_f32 v34, v34, v35
	v_cvt_pk_bf16_f32 v35, v36, v37
	global_store_dwordx2 v241, v[34:35], s[64:65]
	v_cvt_pk_bf16_f32 v38, v38, v39
	v_cvt_pk_bf16_f32 v39, v40, v41
	global_store_dwordx2 v241, v[38:39], s[64:65] offset:512
	v_cvt_pk_bf16_f32 v42, v42, v43
	v_cvt_pk_bf16_f32 v43, v44, v45
	global_store_dwordx2 v241, v[42:43], s[64:65] offset:1024
	v_cvt_pk_bf16_f32 v46, v46, v47
	v_cvt_pk_bf16_f32 v47, v48, v49
	global_store_dwordx2 v241, v[46:47], s[64:65] offset:1536
	s_add_u32 s64, s64, 0x800
	s_addc_u32 s65, s65, 0
	s_waitcnt vmcnt(28)
	v_pk_mul_f32 v[212:213], v[50:51], v[50:51]
	v_pk_fma_f32 v[212:213], v[52:53], v[52:53], v[212:213]
	v_pk_fma_f32 v[212:213], v[54:55], v[54:55], v[212:213]
	v_pk_fma_f32 v[212:213], v[56:57], v[56:57], v[212:213]
	v_pk_fma_f32 v[212:213], v[58:59], v[58:59], v[212:213]
	v_pk_fma_f32 v[212:213], v[60:61], v[60:61], v[212:213]
	v_pk_fma_f32 v[212:213], v[62:63], v[62:63], v[212:213]
	v_pk_fma_f32 v[212:213], v[64:65], v[64:65], v[212:213]
	v_add_f32_e32 v214, v212, v213
	s_nop 1
	v_add_f32_dpp v214, v214, v214 quad_perm:[1,0,3,2] row_mask:0xf bank_mask:0xf
	s_nop 1
	v_add_f32_dpp v214, v214, v214 quad_perm:[2,3,0,1] row_mask:0xf bank_mask:0xf
	s_nop 1
	v_add_f32_dpp v214, v214, v214 row_half_mirror row_mask:0xf bank_mask:0xf
	s_nop 1
	v_add_f32_dpp v214, v214, v214 row_mirror row_mask:0xf bank_mask:0xf
	s_nop 1
	v_readlane_b32 vcc_lo, v214, 0
	v_readlane_b32 vcc_hi, v214, 16
	s_nop 1
	v_mov_b32_e32 v216, vcc_lo
	v_add_f32_e32 v216, vcc_hi, v216
	v_readlane_b32 vcc_lo, v214, 32
	v_readlane_b32 vcc_hi, v214, 48
	s_nop 1
	v_add_f32_e32 v216, vcc_lo, v216
	v_add_f32_e32 v216, vcc_hi, v216
	v_fmamk_f32 v216, v216, 0x3a800000, v174
	v_rsq_f32_e32 v216, v216
	s_nop 0
	v_pk_mul_f32 v[50:51], v[50:51], v[216:217] op_sel_hi:[1,0]
	v_pk_mul_f32 v[52:53], v[52:53], v[216:217] op_sel_hi:[1,0]
	v_pk_mul_f32 v[54:55], v[54:55], v[216:217] op_sel_hi:[1,0]
	v_pk_mul_f32 v[56:57], v[56:57], v[216:217] op_sel_hi:[1,0]
	v_pk_mul_f32 v[58:59], v[58:59], v[216:217] op_sel_hi:[1,0]
	v_pk_mul_f32 v[60:61], v[60:61], v[216:217] op_sel_hi:[1,0]
	v_pk_mul_f32 v[62:63], v[62:63], v[216:217] op_sel_hi:[1,0]
	v_pk_mul_f32 v[64:65], v[64:65], v[216:217] op_sel_hi:[1,0]
	v_pk_mul_f32 v[50:51], v[136:137], v[50:51]
	v_pk_mul_f32 v[52:53], v[138:139], v[52:53]
	v_pk_mul_f32 v[54:55], v[140:141], v[54:55]
	v_pk_mul_f32 v[56:57], v[142:143], v[56:57]
	v_pk_mul_f32 v[58:59], v[144:145], v[58:59]
	v_pk_mul_f32 v[60:61], v[146:147], v[60:61]
	v_pk_mul_f32 v[62:63], v[148:149], v[62:63]
	v_pk_mul_f32 v[64:65], v[150:151], v[64:65]
	v_pk_fma_f32 v[50:51], v[196:197], v[50:51], v[152:153]
	v_pk_fma_f32 v[52:53], v[198:199], v[52:53], v[154:155]
	v_pk_fma_f32 v[54:55], v[200:201], v[54:55], v[156:157]
	v_pk_fma_f32 v[56:57], v[202:203], v[56:57], v[158:159]
	v_pk_fma_f32 v[58:59], v[204:205], v[58:59], v[160:161]
	v_pk_fma_f32 v[60:61], v[206:207], v[60:61], v[162:163]
	v_pk_fma_f32 v[62:63], v[208:209], v[62:63], v[164:165]
	v_pk_fma_f32 v[64:65], v[210:211], v[64:65], v[166:167]
	v_cvt_pk_bf16_f32 v50, v50, v51
	v_cvt_pk_bf16_f32 v51, v52, v53
	global_store_dwordx2 v241, v[50:51], s[64:65]
	v_cvt_pk_bf16_f32 v54, v54, v55
	v_cvt_pk_bf16_f32 v55, v56, v57
	global_store_dwordx2 v241, v[54:55], s[64:65] offset:512
	v_cvt_pk_bf16_f32 v58, v58, v59
	v_cvt_pk_bf16_f32 v59, v60, v61
	global_store_dwordx2 v241, v[58:59], s[64:65] offset:1024
	v_cvt_pk_bf16_f32 v62, v62, v63
	v_cvt_pk_bf16_f32 v63, v64, v65
	global_store_dwordx2 v241, v[62:63], s[64:65] offset:1536
	s_add_u32 s64, s64, 0x800
	s_addc_u32 s65, s65, 0
	s_waitcnt vmcnt(28)
; __device__ __forceinline__ void phase_norm(const Params& p, int l, int which, int nrows) {
;     ...
; #pragma unroll
;     for (int i = 0; i < 4; ++i) {
;       v[i] = *(const float4*)(xr + i * 256 + lane * 4);
;       ss += v[i].x * v[i].x + v[i].y * v[i].y + v[i].z * v[i].z + v[i].w * v[i].w;
;     }
;     ss = wave_sum(ss);
;     const float rstd = rsqrtf(ss * (1.f / 1024.f) + 1e-6f);
; #pragma unroll
;     for (int i = 0; i < 4; ++i) {
;       const int c = i * 256 + lane * 4;
;       const float y0 = (v[i].x * rstd * g4[i].x) * (1.f + c4[i].x) + s4[i].x;
;       const float y1 = (v[i].y * rstd * g4[i].y) * (1.f + c4[i].y) + s4[i].y;
;       const float y2 = (v[i].z * rstd * g4[i].z) * (1.f + c4[i].z) + s4[i].z;
;       const float y3 = (v[i].w * rstd * g4[i].w) * (1.f + c4[i].w) + s4[i].w;
;       u32x2 o; o.x = pack2(y0, y1); o.y = pack2(y2, y3);
;       *(u32x2*)(H + (size_t)r * DM + c) = o;
;     }
	v_pk_mul_f32 v[212:213], v[66:67], v[66:67]
	v_pk_fma_f32 v[212:213], v[68:69], v[68:69], v[212:213]
	v_pk_fma_f32 v[212:213], v[70:71], v[70:71], v[212:213]
	v_pk_fma_f32 v[212:213], v[72:73], v[72:73], v[212:213]
	v_pk_fma_f32 v[212:213], v[74:75], v[74:75], v[212:213]
	v_pk_fma_f32 v[212:213], v[76:77], v[76:77], v[212:213]
	v_pk_fma_f32 v[212:213], v[78:79], v[78:79], v[212:213]
	v_pk_fma_f32 v[212:213], v[80:81], v[80:81], v[212:213]
	v_add_f32_e32 v214, v212, v213
	s_nop 1
	v_add_f32_dpp v214, v214, v214 quad_perm:[1,0,3,2] row_mask:0xf bank_mask:0xf
	s_nop 1
	v_add_f32_dpp v214, v214, v214 quad_perm:[2,3,0,1] row_mask:0xf bank_mask:0xf
	s_nop 1
	v_add_f32_dpp v214, v214, v214 row_half_mirror row_mask:0xf bank_mask:0xf
	s_nop 1
	v_add_f32_dpp v214, v214, v214 row_mirror row_mask:0xf bank_mask:0xf
	s_nop 1
	v_readlane_b32 vcc_lo, v214, 0
	v_readlane_b32 vcc_hi, v214, 16
	s_nop 1
	v_mov_b32_e32 v216, vcc_lo
	v_add_f32_e32 v216, vcc_hi, v216
	v_readlane_b32 vcc_lo, v214, 32
	v_readlane_b32 vcc_hi, v214, 48
	s_nop 1
	v_add_f32_e32 v216, vcc_lo, v216
	v_add_f32_e32 v216, vcc_hi, v216
	v_fmamk_f32 v216, v216, 0x3a800000, v174
	v_rsq_f32_e32 v216, v216
	s_nop 0
	v_pk_mul_f32 v[66:67], v[66:67], v[216:217] op_sel_hi:[1,0]
	v_pk_mul_f32 v[68:69], v[68:69], v[216:217] op_sel_hi:[1,0]
	v_pk_mul_f32 v[70:71], v[70:71], v[216:217] op_sel_hi:[1,0]
	v_pk_mul_f32 v[72:73], v[72:73], v[216:217] op_sel_hi:[1,0]
	v_pk_mul_f32 v[74:75], v[74:75], v[216:217] op_sel_hi:[1,0]
	v_pk_mul_f32 v[76:77], v[76:77], v[216:217] op_sel_hi:[1,0]
	v_pk_mul_f32 v[78:79], v[78:79], v[216:217] op_sel_hi:[1,0]
	v_pk_mul_f32 v[80:81], v[80:81], v[216:217] op_sel_hi:[1,0]
	v_pk_mul_f32 v[66:67], v[136:137], v[66:67]
	v_pk_mul_f32 v[68:69], v[138:139], v[68:69]
	v_pk_mul_f32 v[70:71], v[140:141], v[70:71]
	v_pk_mul_f32 v[72:73], v[142:143], v[72:73]
	v_pk_mul_f32 v[74:75], v[144:145], v[74:75]
	v_pk_mul_f32 v[76:77], v[146:147], v[76:77]
	v_pk_mul_f32 v[78:79], v[148:149], v[78:79]
	v_pk_mul_f32 v[80:81], v[150:151], v[80:81]
	v_pk_fma_f32 v[66:67], v[196:197], v[66:67], v[152:153]
	v_pk_fma_f32 v[68:69], v[198:199], v[68:69], v[154:155]
	v_pk_fma_f32 v[70:71], v[200:201], v[70:71], v[156:157]
	v_pk_fma_f32 v[72:73], v[202:203], v[72:73], v[158:159]
	v_pk_fma_f32 v[74:75], v[204:205], v[74:75], v[160:161]
	v_pk_fma_f32 v[76:77], v[206:207], v[76:77], v[162:163]
	v_pk_fma_f32 v[78:79], v[208:209], v[78:79], v[164:165]
	v_pk_fma_f32 v[80:81], v[210:211], v[80:81], v[166:167]
	v_cvt_pk_bf16_f32 v66, v66, v67
	v_cvt_pk_bf16_f32 v67, v68, v69
	global_store_dwordx2 v241, v[66:67], s[64:65]
	v_cvt_pk_bf16_f32 v70, v70, v71
	v_cvt_pk_bf16_f32 v71, v72, v73
	global_store_dwordx2 v241, v[70:71], s[64:65] offset:512
	v_cvt_pk_bf16_f32 v74, v74, v75
	v_cvt_pk_bf16_f32 v75, v76, v77
	global_store_dwordx2 v241, v[74:75], s[64:65] offset:1024
	v_cvt_pk_bf16_f32 v78, v78, v79
	v_cvt_pk_bf16_f32 v79, v80, v81
	global_store_dwordx2 v241, v[78:79], s[64:65] offset:1536
	s_add_u32 s64, s64, 0x800
	s_addc_u32 s65, s65, 0
	s_waitcnt vmcnt(28)
	v_pk_mul_f32 v[212:213], v[82:83], v[82:83]
	v_pk_fma_f32 v[212:213], v[84:85], v[84:85], v[212:213]
	v_pk_fma_f32 v[212:213], v[86:87], v[86:87], v[212:213]
	v_pk_fma_f32 v[212:213], v[88:89], v[88:89], v[212:213]
	v_pk_fma_f32 v[212:213], v[92:93], v[92:93], v[212:213]
	v_pk_fma_f32 v[212:213], v[94:95], v[94:95], v[212:213]
	v_pk_fma_f32 v[212:213], v[96:97], v[96:97], v[212:213]
	v_pk_fma_f32 v[212:213], v[98:99], v[98:99], v[212:213]
	v_add_f32_e32 v214, v212, v213
	s_nop 1
	v_add_f32_dpp v214, v214, v214 quad_perm:[1,0,3,2] row_mask:0xf bank_mask:0xf
	s_nop 1
	v_add_f32_dpp v214, v214, v214 quad_perm:[2,3,0,1] row_mask:0xf bank_mask:0xf
	s_nop 1
	v_add_f32_dpp v214, v214, v214 row_half_mirror row_mask:0xf bank_mask:0xf
	s_nop 1
	v_add_f32_dpp v214, v214, v214 row_mirror row_mask:0xf bank_mask:0xf
	s_nop 1
	v_readlane_b32 vcc_lo, v214, 0
	v_readlane_b32 vcc_hi, v214, 16
	s_nop 1
	v_mov_b32_e32 v216, vcc_lo
	v_add_f32_e32 v216, vcc_hi, v216
	v_readlane_b32 vcc_lo, v214, 32
	v_readlane_b32 vcc_hi, v214, 48
	s_nop 1
	v_add_f32_e32 v216, vcc_lo, v216
	v_add_f32_e32 v216, vcc_hi, v216
	v_fmamk_f32 v216, v216, 0x3a800000, v174
	v_rsq_f32_e32 v216, v216
	s_nop 0
	v_pk_mul_f32 v[82:83], v[82:83], v[216:217] op_sel_hi:[1,0]
	v_pk_mul_f32 v[84:85], v[84:85], v[216:217] op_sel_hi:[1,0]
	v_pk_mul_f32 v[86:87], v[86:87], v[216:217] op_sel_hi:[1,0]
	v_pk_mul_f32 v[88:89], v[88:89], v[216:217] op_sel_hi:[1,0]
	v_pk_mul_f32 v[92:93], v[92:93], v[216:217] op_sel_hi:[1,0]
	v_pk_mul_f32 v[94:95], v[94:95], v[216:217] op_sel_hi:[1,0]
	v_pk_mul_f32 v[96:97], v[96:97], v[216:217] op_sel_hi:[1,0]
	v_pk_mul_f32 v[98:99], v[98:99], v[216:217] op_sel_hi:[1,0]
	v_pk_mul_f32 v[82:83], v[136:137], v[82:83]
	v_pk_mul_f32 v[84:85], v[138:139], v[84:85]
	v_pk_mul_f32 v[86:87], v[140:141], v[86:87]
	v_pk_mul_f32 v[88:89], v[142:143], v[88:89]
	v_pk_mul_f32 v[92:93], v[144:145], v[92:93]
	v_pk_mul_f32 v[94:95], v[146:147], v[94:95]
	v_pk_mul_f32 v[96:97], v[148:149], v[96:97]
	v_pk_mul_f32 v[98:99], v[150:151], v[98:99]
	v_pk_fma_f32 v[82:83], v[196:197], v[82:83], v[152:153]
	v_pk_fma_f32 v[84:85], v[198:199], v[84:85], v[154:155]
	v_pk_fma_f32 v[86:87], v[200:201], v[86:87], v[156:157]
	v_pk_fma_f32 v[88:89], v[202:203], v[88:89], v[158:159]
	v_pk_fma_f32 v[92:93], v[204:205], v[92:93], v[160:161]
	v_pk_fma_f32 v[94:95], v[206:207], v[94:95], v[162:163]
	v_pk_fma_f32 v[96:97], v[208:209], v[96:97], v[164:165]
	v_pk_fma_f32 v[98:99], v[210:211], v[98:99], v[166:167]
	v_cvt_pk_bf16_f32 v82, v82, v83
	v_cvt_pk_bf16_f32 v83, v84, v85
	global_store_dwordx2 v241, v[82:83], s[64:65]
	v_cvt_pk_bf16_f32 v86, v86, v87
	v_cvt_pk_bf16_f32 v87, v88, v89
	global_store_dwordx2 v241, v[86:87], s[64:65] offset:512
	v_cvt_pk_bf16_f32 v92, v92, v93
	v_cvt_pk_bf16_f32 v93, v94, v95
	global_store_dwordx2 v241, v[92:93], s[64:65] offset:1024
	v_cvt_pk_bf16_f32 v96, v96, v97
	v_cvt_pk_bf16_f32 v97, v98, v99
	global_store_dwordx2 v241, v[96:97], s[64:65] offset:1536
	s_add_u32 s64, s64, 0x800
	s_addc_u32 s65, s65, 0
	s_waitcnt vmcnt(28)
; __device__ __forceinline__ void phase_norm(const Params& p, int l, int which, int nrows) {
;     ...
; #pragma unroll
;     for (int i = 0; i < 4; ++i) {
;       v[i] = *(const float4*)(xr + i * 256 + lane * 4);
;       ss += v[i].x * v[i].x + v[i].y * v[i].y + v[i].z * v[i].z + v[i].w * v[i].w;
;     }
;     ss = wave_sum(ss);
;     const float rstd = rsqrtf(ss * (1.f / 1024.f) + 1e-6f);
; #pragma unroll
;     for (int i = 0; i < 4; ++i) {
;       const int c = i * 256 + lane * 4;
;       const float y0 = (v[i].x * rstd * g4[i].x) * (1.f + c4[i].x) + s4[i].x;
;       const float y1 = (v[i].y * rstd * g4[i].y) * (1.f + c4[i].y) + s4[i].y;
;       const float y2 = (v[i].z * rstd * g4[i].z) * (1.f + c4[i].z) + s4[i].z;
;       const float y3 = (v[i].w * rstd * g4[i].w) * (1.f + c4[i].w) + s4[i].w;
;       u32x2 o; o.x = pack2(y0, y1); o.y = pack2(y2, y3);
;       *(u32x2*)(H + (size_t)r * DM + c) = o;
;     }
	v_pk_mul_f32 v[212:213], v[100:101], v[100:101]
	v_pk_fma_f32 v[212:213], v[102:103], v[102:103], v[212:213]
	v_pk_fma_f32 v[212:213], v[104:105], v[104:105], v[212:213]
	v_pk_fma_f32 v[212:213], v[106:107], v[106:107], v[212:213]
	v_pk_fma_f32 v[212:213], v[108:109], v[108:109], v[212:213]
	v_pk_fma_f32 v[212:213], v[110:111], v[110:111], v[212:213]
	v_pk_fma_f32 v[212:213], v[112:113], v[112:113], v[212:213]
	v_pk_fma_f32 v[212:213], v[114:115], v[114:115], v[212:213]
	v_add_f32_e32 v214, v212, v213
	s_nop 1
	v_add_f32_dpp v214, v214, v214 quad_perm:[1,0,3,2] row_mask:0xf bank_mask:0xf
	s_nop 1
	v_add_f32_dpp v214, v214, v214 quad_perm:[2,3,0,1] row_mask:0xf bank_mask:0xf
	s_nop 1
	v_add_f32_dpp v214, v214, v214 row_half_mirror row_mask:0xf bank_mask:0xf
	s_nop 1
	v_add_f32_dpp v214, v214, v214 row_mirror row_mask:0xf bank_mask:0xf
	s_nop 1
	v_readlane_b32 vcc_lo, v214, 0
	v_readlane_b32 vcc_hi, v214, 16
	s_nop 1
	v_mov_b32_e32 v216, vcc_lo
	v_add_f32_e32 v216, vcc_hi, v216
	v_readlane_b32 vcc_lo, v214, 32
	v_readlane_b32 vcc_hi, v214, 48
	s_nop 1
	v_add_f32_e32 v216, vcc_lo, v216
	v_add_f32_e32 v216, vcc_hi, v216
	v_fmamk_f32 v216, v216, 0x3a800000, v174
	v_rsq_f32_e32 v216, v216
	s_nop 0
	v_pk_mul_f32 v[100:101], v[100:101], v[216:217] op_sel_hi:[1,0]
	v_pk_mul_f32 v[102:103], v[102:103], v[216:217] op_sel_hi:[1,0]
	v_pk_mul_f32 v[104:105], v[104:105], v[216:217] op_sel_hi:[1,0]
	v_pk_mul_f32 v[106:107], v[106:107], v[216:217] op_sel_hi:[1,0]
	v_pk_mul_f32 v[108:109], v[108:109], v[216:217] op_sel_hi:[1,0]
	v_pk_mul_f32 v[110:111], v[110:111], v[216:217] op_sel_hi:[1,0]
	v_pk_mul_f32 v[112:113], v[112:113], v[216:217] op_sel_hi:[1,0]
	v_pk_mul_f32 v[114:115], v[114:115], v[216:217] op_sel_hi:[1,0]
	v_pk_mul_f32 v[100:101], v[136:137], v[100:101]
	v_pk_mul_f32 v[102:103], v[138:139], v[102:103]
	v_pk_mul_f32 v[104:105], v[140:141], v[104:105]
	v_pk_mul_f32 v[106:107], v[142:143], v[106:107]
	v_pk_mul_f32 v[108:109], v[144:145], v[108:109]
	v_pk_mul_f32 v[110:111], v[146:147], v[110:111]
	v_pk_mul_f32 v[112:113], v[148:149], v[112:113]
	v_pk_mul_f32 v[114:115], v[150:151], v[114:115]
	v_pk_fma_f32 v[100:101], v[196:197], v[100:101], v[152:153]
	v_pk_fma_f32 v[102:103], v[198:199], v[102:103], v[154:155]
	v_pk_fma_f32 v[104:105], v[200:201], v[104:105], v[156:157]
	v_pk_fma_f32 v[106:107], v[202:203], v[106:107], v[158:159]
	v_pk_fma_f32 v[108:109], v[204:205], v[108:109], v[160:161]
	v_pk_fma_f32 v[110:111], v[206:207], v[110:111], v[162:163]
	v_pk_fma_f32 v[112:113], v[208:209], v[112:113], v[164:165]
	v_pk_fma_f32 v[114:115], v[210:211], v[114:115], v[166:167]
	v_cvt_pk_bf16_f32 v100, v100, v101
	v_cvt_pk_bf16_f32 v101, v102, v103
	global_store_dwordx2 v241, v[100:101], s[64:65]
	v_cvt_pk_bf16_f32 v104, v104, v105
	v_cvt_pk_bf16_f32 v105, v106, v107
	global_store_dwordx2 v241, v[104:105], s[64:65] offset:512
	v_cvt_pk_bf16_f32 v108, v108, v109
	v_cvt_pk_bf16_f32 v109, v110, v111
	global_store_dwordx2 v241, v[108:109], s[64:65] offset:1024
	v_cvt_pk_bf16_f32 v112, v112, v113
	v_cvt_pk_bf16_f32 v113, v114, v115
	global_store_dwordx2 v241, v[112:113], s[64:65] offset:1536
	s_add_u32 s64, s64, 0x800
	s_addc_u32 s65, s65, 0
	s_waitcnt vmcnt(28)
	v_pk_mul_f32 v[212:213], v[116:117], v[116:117]
	v_pk_fma_f32 v[212:213], v[118:119], v[118:119], v[212:213]
	v_pk_fma_f32 v[212:213], v[120:121], v[120:121], v[212:213]
	v_pk_fma_f32 v[212:213], v[122:123], v[122:123], v[212:213]
	v_pk_fma_f32 v[212:213], v[124:125], v[124:125], v[212:213]
	v_pk_fma_f32 v[212:213], v[126:127], v[126:127], v[212:213]
	v_pk_fma_f32 v[212:213], v[128:129], v[128:129], v[212:213]
	v_pk_fma_f32 v[212:213], v[130:131], v[130:131], v[212:213]
	v_add_f32_e32 v214, v212, v213
	s_nop 1
	v_add_f32_dpp v214, v214, v214 quad_perm:[1,0,3,2] row_mask:0xf bank_mask:0xf
	s_nop 1
	v_add_f32_dpp v214, v214, v214 quad_perm:[2,3,0,1] row_mask:0xf bank_mask:0xf
	s_nop 1
	v_add_f32_dpp v214, v214, v214 row_half_mirror row_mask:0xf bank_mask:0xf
	s_nop 1
	v_add_f32_dpp v214, v214, v214 row_mirror row_mask:0xf bank_mask:0xf
	s_nop 1
	v_readlane_b32 vcc_lo, v214, 0
	v_readlane_b32 vcc_hi, v214, 16
	s_nop 1
	v_mov_b32_e32 v216, vcc_lo
	v_add_f32_e32 v216, vcc_hi, v216
	v_readlane_b32 vcc_lo, v214, 32
	v_readlane_b32 vcc_hi, v214, 48
	s_nop 1
	v_add_f32_e32 v216, vcc_lo, v216
	v_add_f32_e32 v216, vcc_hi, v216
	v_fmamk_f32 v216, v216, 0x3a800000, v174
	v_rsq_f32_e32 v216, v216
	s_nop 0
	v_pk_mul_f32 v[116:117], v[116:117], v[216:217] op_sel_hi:[1,0]
	v_pk_mul_f32 v[118:119], v[118:119], v[216:217] op_sel_hi:[1,0]
	v_pk_mul_f32 v[120:121], v[120:121], v[216:217] op_sel_hi:[1,0]
	v_pk_mul_f32 v[122:123], v[122:123], v[216:217] op_sel_hi:[1,0]
	v_pk_mul_f32 v[124:125], v[124:125], v[216:217] op_sel_hi:[1,0]
	v_pk_mul_f32 v[126:127], v[126:127], v[216:217] op_sel_hi:[1,0]
	v_pk_mul_f32 v[128:129], v[128:129], v[216:217] op_sel_hi:[1,0]
	v_pk_mul_f32 v[130:131], v[130:131], v[216:217] op_sel_hi:[1,0]
	v_pk_mul_f32 v[116:117], v[136:137], v[116:117]
	v_pk_mul_f32 v[118:119], v[138:139], v[118:119]
	v_pk_mul_f32 v[120:121], v[140:141], v[120:121]
	v_pk_mul_f32 v[122:123], v[142:143], v[122:123]
	v_pk_mul_f32 v[124:125], v[144:145], v[124:125]
	v_pk_mul_f32 v[126:127], v[146:147], v[126:127]
	v_pk_mul_f32 v[128:129], v[148:149], v[128:129]
	v_pk_mul_f32 v[130:131], v[150:151], v[130:131]
	v_pk_fma_f32 v[116:117], v[196:197], v[116:117], v[152:153]
	v_pk_fma_f32 v[118:119], v[198:199], v[118:119], v[154:155]
	v_pk_fma_f32 v[120:121], v[200:201], v[120:121], v[156:157]
	v_pk_fma_f32 v[122:123], v[202:203], v[122:123], v[158:159]
	v_pk_fma_f32 v[124:125], v[204:205], v[124:125], v[160:161]
	v_pk_fma_f32 v[126:127], v[206:207], v[126:127], v[162:163]
	v_pk_fma_f32 v[128:129], v[208:209], v[128:129], v[164:165]
	v_pk_fma_f32 v[130:131], v[210:211], v[130:131], v[166:167]
	v_cvt_pk_bf16_f32 v116, v116, v117
	v_cvt_pk_bf16_f32 v117, v118, v119
	global_store_dwordx2 v241, v[116:117], s[64:65]
	v_cvt_pk_bf16_f32 v120, v120, v121
	v_cvt_pk_bf16_f32 v121, v122, v123
	global_store_dwordx2 v241, v[120:121], s[64:65] offset:512
	v_cvt_pk_bf16_f32 v124, v124, v125
	v_cvt_pk_bf16_f32 v125, v126, v127
	global_store_dwordx2 v241, v[124:125], s[64:65] offset:1024
	v_cvt_pk_bf16_f32 v128, v128, v129
	v_cvt_pk_bf16_f32 v129, v130, v131
	global_store_dwordx2 v241, v[128:129], s[64:65] offset:1536
	s_add_u32 s64, s64, 0x800
	s_addc_u32 s65, s65, 0
	s_branch .Lnu_next

; __device__ __forceinline__ void phase_norm(const Params& p, int l, int which, int nrows) {
;     ...
;   const int nw = gridDim.x * 4, gw = blockIdx.x * 4 + (tidq >> 6);
;   const int rpw = (nrows + nw - 1) / nw;
;   const int r0 = gw * rpw, r1 = (r0 + rpw < nrows) ? r0 + rpw : nrows;
;   float4 g4[4], s4[4], c4[4];
; #pragma unroll
;   for (int i = 0; i < 4; ++i) g4[i] = *(const float4*)(g + i * 256 + lane * 4);
;   int cur_bi = -1;
;   for (int r = r0; r < r1; ++r) {
;     const float* xr = xrow_ptr(p, from_input, r);
;     const int bi = mod_idx(r);
;     if (bi != cur_bi) {
;       const float* sh = mods_ptr(p, l, bi, which * 3);
; #pragma unroll
;       for (int i = 0; i < 4; ++i) { s4[i] = *(const float4*)(sh + i * 256 + lane * 4); c4[i] = *(const float4*)(sh + 1024 + i * 256 + lane * 4); }
;       cur_bi = bi;
; __global__ void __launch_bounds__(256, 2) fwd_megakernel(Params p) {
;     ...
;     if (k == 0 || k == 3 || k == 11) {
;       const int which = (k == 0) ? 0 : (k == 3) ? 1 : 2;
;       for (int rpt = 0; rpt < ((PROBE_MASK & 4) ? 2 : 1); ++rpt) phase_norm(p, l, which, k == 11 ? mr2 : NTOK);
.LBB0_331:
	s_andn2_b64 vcc, exec, s[34:35]
	s_cbranch_vccnz .LBB0_348
	s_cmp_eq_u32 s77, 3
	s_cbranch_scc1 .LBB0_348
	s_cmp_eq_u32 s77, 11
	s_cselect_b32 s22, s22, 0x9000
	v_readlane_b32 s23, v251, 6
	v_mov_b32_e32 v0, v172
	s_add_i32 s23, s23, s22
	v_readlane_b32 s30, v251, 5
	s_waitcnt vmcnt(3)
	v_ashrrev_i32_e32 v2, 6, v0
	s_ashr_i32 s34, s23, 31
	v_add_u32_e32 v2, s30, v2
	v_readlane_b32 s30, v250, 19
	s_xor_b32 s34, s34, s30
	s_abs_i32 s23, s23
	v_readlane_b32 s30, v250, 21
	s_mul_hi_u32 s35, s23, s30
	v_readlane_b32 s30, v250, 20
	s_mul_i32 s36, s35, s30
	s_sub_i32 s23, s23, s36
	s_add_i32 s36, s35, 1
	s_sub_i32 s37, s23, s30
	s_cmp_ge_u32 s23, s30
	s_cselect_b32 s35, s36, s35
	s_cselect_b32 s23, s37, s23
	s_add_i32 s36, s35, 1
	s_cmp_ge_u32 s23, s30
	s_cselect_b32 s23, s36, s35
	s_xor_b32 s23, s23, s34
	s_sub_i32 s23, s23, s34
	v_mul_lo_u32 v50, s23, v2
	v_add_u32_e32 v2, s23, v50
	v_min_i32_e32 v53, s22, v2
	v_cmp_lt_i32_e32 vcc, v50, v53
	s_and_saveexec_b64 s[34:35], vcc
	s_cbranch_execz .LBB0_347
	v_readlane_b32 s40, v250, 31
	s_cmp_eq_u32 s77, 3
	v_readlane_b32 s41, v250, 32
	s_cselect_b32 s36, 1, 2
	s_and_b64 s[22:23], exec, s[40:41]
	s_load_dwordx2 s[30:31], s[0:1], 0x30
	s_cselect_b32 s36, s36, 0
	s_and_b64 s[22:23], s[28:29], exec
	s_cselect_b32 s22, 3, 0
	s_add_i32 s22, s36, s22
	s_lshl_b32 s22, s22, 12
	v_lshlrev_b32_e32 v2, 2, v0
	s_waitcnt lgkmcnt(0)
	s_add_u32 s22, s30, s22
	v_and_b32_e32 v52, 0xfc, v2
	s_addc_u32 s23, s31, 0
	s_waitcnt vmcnt(0)
	v_lshlrev_b32_e32 v14, 2, v52
	global_load_dwordx4 v[2:5], v14, s[22:23]
	global_load_dwordx4 v[6:9], v14, s[22:23] offset:1024
	global_load_dwordx4 v[10:13], v14, s[22:23] offset:2048
	s_nop 0
	global_load_dwordx4 v[14:17], v14, s[22:23] offset:3072
	v_and_b32_e32 v18, 64, v178
	v_add_u32_e32 v18, 64, v18
	v_xor_b32_e32 v19, 32, v178
	v_cmp_lt_i32_e32 vcc, v19, v18
	v_ashrrev_i32_e32 v51, 31, v50
	s_nor_b64 s[30:31], s[28:29], s[40:41]
	v_cndmask_b32_e32 v19, v178, v19, vcc
	v_lshlrev_b32_e32 v60, 2, v19
	v_xor_b32_e32 v19, 16, v178
	v_cmp_lt_i32_e32 vcc, v19, v18
	v_and_b32_e32 v0, 63, v0
	s_and_b64 s[28:29], s[28:29], exec
	v_cndmask_b32_e32 v19, v178, v19, vcc
	v_lshlrev_b32_e32 v61, 2, v19
	v_xor_b32_e32 v19, 8, v178
	v_cmp_lt_i32_e32 vcc, v19, v18
	s_mul_i32 s22, s36, 3
	s_cselect_b32 s23, 17, 0
	v_cndmask_b32_e32 v19, v178, v19, vcc
	v_lshlrev_b32_e32 v62, 2, v19
	v_xor_b32_e32 v19, 4, v178
	v_cmp_lt_i32_e32 vcc, v19, v18
	v_mov_b32_e32 v66, -1
	s_mov_b64 s[28:29], 0
	v_cndmask_b32_e32 v19, v178, v19, vcc
	v_lshlrev_b32_e32 v63, 2, v19
	v_xor_b32_e32 v19, 2, v178
	v_cmp_lt_i32_e32 vcc, v19, v18
	s_nop 1
	v_cndmask_b32_e32 v19, v178, v19, vcc
	v_lshlrev_b32_e32 v64, 2, v19
	v_xor_b32_e32 v19, 1, v178
	v_cmp_lt_i32_e32 vcc, v19, v18
	s_nop 1
	v_cndmask_b32_e32 v18, v178, v19, vcc
	v_lshlrev_b32_e32 v65, 2, v18
	v_lshlrev_b64 v[18:19], 11, v[50:51]
	v_lshl_or_b32 v18, v0, 3, v18
	v_lshl_add_u64 v[54:55], v[92:93], 0, v[18:19]
	s_branch .LBB0_335
